# mix2 scan: the two remaining full waits on the load side removed (measurement 1)
# speedup vs baseline: 1.0041x; 1.0004x over previous
.LBB0_902:
	v_cmp_lt_u32_e64 s[72:73], s17, v184
	v_lshl_add_u64 v[208:209], v[170:171], 0, v[34:35]
	s_and_saveexec_b64 s[12:13], s[72:73]
	s_cbranch_execz .LBB0_904
	v_add_co_u32_e32 v106, vcc, 0x41100000, v208
	s_nop 1
	v_addc_co_u32_e32 v107, vcc, 0, v209, vcc
	global_load_dwordx2 v[106:107], v[106:107], off

.LBB0_932:
	s_or_b64 exec, exec, s[12:13]
	s_add_i32 s17, s17, 1
	v_cmp_lt_u32_e64 s[42:43], s17, v184
	v_lshl_add_u64 v[172:173], v[72:73], 0, v[34:35]
	s_and_saveexec_b64 s[12:13], s[42:43]
	s_cbranch_execz .LBB0_949
	v_add_co_u32_e32 v76, vcc, 0x41100000, v172
	s_nop 1
	v_addc_co_u32_e32 v77, vcc, 0, v173, vcc
	global_load_dwordx2 v[76:77], v[76:77], off
	s_or_b64 exec, exec, s[12:13]
	s_and_saveexec_b64 s[12:13], s[72:73]
	s_cbranch_execnz .LBB0_950

.LBB0_978:
	v_cmp_lt_u32_e64 s[40:41], s17, v184
	v_lshl_add_u64 v[36:37], s[26:27], 0, v[172:173]
	s_and_saveexec_b64 s[12:13], s[40:41]
	s_cbranch_execz .LBB0_980
	v_add_co_u32_e32 v66, vcc, 0x3e800000, v36
	v_lshl_add_u64 v[68:69], s[26:27], 0, v[210:211]
	s_nop 0
	v_addc_co_u32_e32 v67, vcc, 0, v37, vcc
	global_load_dwordx2 v[74:75], v[66:67], off
	s_nop 0
	global_load_dwordx4 v[66:69], v[68:69], off

.LBB0_1008:
	s_or_b64 exec, exec, s[12:13]
	s_add_i32 s17, s17, 1
	v_cmp_lt_u32_e64 s[70:71], s17, v184
	v_lshl_add_u64 v[240:241], s[26:27], 0, v[142:143]
	s_and_saveexec_b64 s[12:13], s[70:71]
	s_cbranch_execz .LBB0_1025
	v_add_co_u32_e32 v2, vcc, 0x3e800000, v240
	v_lshl_add_u64 v[4:5], s[26:27], 0, v[174:175]
	s_nop 0
	v_addc_co_u32_e32 v3, vcc, 0, v241, vcc
	global_load_dwordx2 v[136:137], v[2:3], off
	s_nop 0
	global_load_dwordx4 v[2:5], v[4:5], off
	s_or_b64 exec, exec, s[12:13]
	s_and_saveexec_b64 s[12:13], s[40:41]
	s_cbranch_execnz .LBB0_1026
